# E62: E61 + prompt-FoX LDS stage-in addresses computed once per unit, buffer half chosen by immediate offset on two parity paths (4 VALU + 2 SALU fewer per tile)
# speedup vs baseline: 1.0392x; 1.0018x over previous
.LBB0_1387:
	s_or_b64 exec, exec, s[18:19]
	s_movk_i32 s15, 0x90
	v_mul_lo_u32 v147, v4, s15
	v_lshlrev_b32_e32 v153, 4, v8
	v_add3_u32 v8, 0, v147, v153
	s_waitcnt lgkmcnt(0)
	s_barrier
	s_barrier
	ds_write_b128 v8, v[130:133]
	v_mad_u64_u32 v[8:9], s[16:17], v4, 48, v[8:9]
	v_mul_lo_u32 v174, v6, s15
	v_lshlrev_b32_e32 v175, 4, v5
	ds_write_b128 v8, v[134:137] offset:18432
	v_add3_u32 v8, 0, v174, v175
	v_lshrrev_b32_e32 v2, 2, v2
	s_cmp_lt_i32 s13, s12
	s_movk_i32 s18, 0xc0
	ds_write_b128 v8, v[138:141]
	v_mad_u64_u32 v[8:9], s[16:17], v6, 48, v[8:9]
	v_and_or_b32 v5, v2, 3, v216
	v_and_or_b32 v2, v2, 4, v225
	v_mov_b32_e32 v16, v3
	v_mov_b32_e32 v17, v3
	s_cselect_b64 s[84:85], -1, 0
	s_add_i32 s14, s9, 0x7f
	s_add_i32 s13, s13, s8
	v_mul_lo_u32 v173, v4, s18
	v_mul_lo_u32 v191, v6, s18
	ds_write_b128 v8, v[142:145] offset:18432
	v_lshlrev_b32_e32 v193, 3, v2
	v_mul_u32_u24_e32 v194, 0xc0, v5
	v_add_u32_e32 v196, 0x80, v6
	v_add_u32_e32 v197, 0x80, v4
	v_mov_b32_e32 v2, v3
	v_mov_b32_e32 v4, v3
	v_mov_b32_e32 v5, v3
	v_mov_b32_e32 v6, v3
	v_mov_b32_e32 v7, v3
	v_mov_b32_e32 v8, v3
	v_mov_b32_e32 v9, v3
	v_mov_b32_e32 v10, v3
	v_mov_b32_e32 v11, v3
	v_mov_b32_e32 v12, v3
	v_mov_b32_e32 v13, v3
	v_mov_b32_e32 v14, v3
	v_mov_b32_e32 v15, v3
	v_mov_b64_e32 v[32:33], v[16:17]
	v_mov_b64_e32 v[48:49], v[16:17]
	s_lshr_b32 s14, s14, 7
	s_movk_i32 s72, 0x90
	s_movk_i32 s73, 0xc0
	s_add_i32 s15, s13, 31
	v_add_u32_e32 v195, s13, v188
	s_mov_b32 s16, 0
	v_mov_b32_e32 v158, 0xf149f2ca
	v_mov_b32_e32 v192, 0
	v_mov_b32_e32 v198, v187
	v_mov_b64_e32 v[30:31], v[14:15]
	v_mov_b64_e32 v[28:29], v[12:13]
	v_mov_b64_e32 v[26:27], v[10:11]
	v_mov_b64_e32 v[24:25], v[8:9]
	v_mov_b64_e32 v[22:23], v[6:7]
	v_mov_b64_e32 v[20:21], v[4:5]
	v_mov_b64_e32 v[18:19], v[2:3]
	v_mov_b64_e32 v[46:47], v[14:15]
	v_mov_b64_e32 v[44:45], v[12:13]
	v_mov_b64_e32 v[42:43], v[10:11]
	v_mov_b64_e32 v[40:41], v[8:9]
	v_mov_b64_e32 v[38:39], v[6:7]
	v_mov_b64_e32 v[36:37], v[4:5]
	v_mov_b64_e32 v[34:35], v[2:3]
	s_mov_b32 s18, 0
	s_waitcnt lgkmcnt(0)
	s_barrier
	v_mov_b32_e32 v4, v197
	v_ashrrev_i32_e32 v5, 31, v4
	v_lshlrev_b64 v[4:5], 9, v[4:5]
	v_lshl_add_u64 v[4:5], v[4:5], 0, v[148:149]
	v_lshlrev_b64 v[4:5], 1, v[4:5]
	v_lshl_add_u64 v[248:249], s[64:65], 0, v[4:5]
	v_lshl_add_u64 v[246:247], s[66:67], 0, v[4:5]
	v_mov_b32_e32 v4, v196
	v_ashrrev_i32_e32 v5, 31, v4
	v_lshlrev_b64 v[4:5], 9, v[4:5]
	v_lshl_add_u64 v[4:5], v[4:5], 0, v[156:157]
	v_lshlrev_b64 v[4:5], 1, v[4:5]
	v_lshl_add_u64 v[250:251], s[64:65], 0, v[4:5]
	v_lshl_add_u64 v[252:253], s[66:67], 0, v[4:5]
	s_mov_b32 s100, 0x20000
	s_mov_b32 s101, 0
	v_add_u32_e32 v200, v147, v153
	v_add_u32_e32 v201, v191, v175
	v_add_u32_e32 v202, v174, v175
	v_add_u32_e32 v203, v173, v153

.LBB0_1396:
	s_andn2_b64 vcc, exec, s[90:91]
	s_cbranch_vccnz .LBB0_1398
	s_bitcmp1_b32 s17, 0
	s_cbranch_scc1 .Lfxw_odd
	s_waitcnt vmcnt(2)
	ds_write_b128 v200, v[130:133]
	ds_write_b128 v203, v[134:137] offset:18432
	s_waitcnt vmcnt(1)
	ds_write_b128 v202, v[138:141]
	s_waitcnt vmcnt(0)
	ds_write_b128 v201, v[142:145] offset:18432
	s_branch .LBB0_1398
.Lfxw_odd:
	s_waitcnt vmcnt(2)
	ds_write_b128 v200, v[130:133] offset:43008
	ds_write_b128 v203, v[134:137] offset:61440
	s_waitcnt vmcnt(1)
	ds_write_b128 v202, v[138:141] offset:43008
	s_waitcnt vmcnt(0)
	ds_write_b128 v201, v[142:145] offset:61440
